# v20 plus skipping the two already-retired DMA waits of the first K-loop trip after each GEMM epilogue
# baseline (speedup 1.0000x reference)
; #define PG8_STAGE(bufoff, gbase, voff) do { _Pragma("unroll") for (int _i = 0; _i < 2; ++_i) \
;         __builtin_amdgcn_global_load_lds((const unsigned*)((const char*)(gbase) + (voff)[_i]), (PG8_LAS unsigned*)(lds + (bufoff) + ldsw + _i * 8192), 16, 0, 0); } while (0)
; #define PG8_LDA(dst, b, h) do { _Pragma("unroll") for (int m = 0; m < 4; ++m) _Pragma("unroll") for (int k = 0; k < 2; ++k) dst[m][k] = *(const PG8_LAS bf16x8*)(lds + PG8_SA(b, h) + aoff + m * 2048 + k * 1024); } while (0)
; #define PG8_LDB(dst, b, h) do { _Pragma("unroll") for (int n = 0; n < 2; ++n) _Pragma("unroll") for (int k = 0; k < 2; ++k) dst[n][k] = *(const PG8_LAS bf16x8*)(lds + PG8_SB(b, h) + boff + n * 2048 + k * 1024); } while (0)
; #define PG8_MMA(ai, bj, At, Bt) do { __builtin_amdgcn_s_setprio(1); _Pragma("unroll") for (int m = 0; m < 4; ++m) _Pragma("unroll") for (int n = 0; n < 2; ++n) _Pragma("unroll") for (int k = 0; k < 2; ++k) \
;         acc[ai][bj][m][n] = __builtin_amdgcn_mfma_f32_16x16x32_bf16(Bt[n][k], At[m][k], acc[ai][bj][m][n], 0, 0, 0); __builtin_amdgcn_s_setprio(0); } while (0)
; #define PG8_WAIT_V(n) asm volatile("s_waitcnt vmcnt(" #n ")" ::: "memory")
; #define PG8_WAIT_L(n) asm volatile("s_waitcnt lgkmcnt(" #n ")" ::: "memory")
; #define PG8_BAR __builtin_amdgcn_s_barrier()
; #define PG8_SCHED __builtin_amdgcn_sched_barrier(0)
; template <class Epi, class Sched, bool ALIGN_EPI = false, bool SP2 = false>
; __device__ __forceinline__ void gemm_phase(PG8_LAS unsigned char* lds, const Gemm g, const Sched& S, const Epi& E, const int wave_s) {
;     ...
;             PG8_WAIT_V(8); PG8_WAIT_L(0); PG8_BAR; PG8_MMA(1, 0, At, B0); PG8_MMA(1, 1, At, B1); PG8_BAR; PG8_SCHED;
;             PG8_LDB(B0, 1, 0); PG8_LDB(B1, 1, 1); PG8_SCHED; PG8_LDA(At, 1, 0); PG8_STAGE(PG8_SA(0, 1), a2 + hA, voffA);
;             PG8_WAIT_V(8); PG8_WAIT_L(0); PG8_BAR; PG8_MMA(0, 0, At, B0); PG8_MMA(0, 1, At, B1); PG8_BAR; PG8_SCHED;
;             PG8_LDA(At, 1, 1); PG8_STAGE(PG8_SB(1, 0), b3, voffB); PG8_STAGE(PG8_SB(1, 1), b3 + hB, voffB); PG8_STAGE(PG8_SA(1, 0), a3, voffA);
;             PG8_WAIT_V(8); PG8_WAIT_L(0); PG8_BAR; PG8_MMA(1, 0, At, B0); PG8_MMA(1, 1, At, B1); PG8_BAR; PG8_SCHED;
.Lrlx_P3_1:
	s_mov_b64 s[100:101], 0
	s_waitcnt lgkmcnt(0)
	s_barrier
	s_setprio 1
	s_waitcnt lgkmcnt(0)
	v_mfma_f32_16x16x32_bf16 v[60:63], v[128:131], v[184:187], v[60:63]
	v_mfma_f32_16x16x32_bf16 v[56:59], v[160:163], v[184:187], v[56:59]
	v_mfma_f32_16x16x32_bf16 v[44:47], v[128:131], v[192:195], v[44:47]
	v_mfma_f32_16x16x32_bf16 v[40:43], v[160:163], v[192:195], v[40:43]
	v_mfma_f32_16x16x32_bf16 v[28:31], v[128:131], v[200:203], v[28:31]
	v_mfma_f32_16x16x32_bf16 v[24:27], v[160:163], v[200:203], v[24:27]
	v_mfma_f32_16x16x32_bf16 v[12:15], v[128:131], v[208:211], v[12:15]
	v_mfma_f32_16x16x32_bf16 v[8:11], v[160:163], v[208:211], v[8:11]
	v_mfma_f32_16x16x32_bf16 v[60:63], v[156:159], v[188:191], v[60:63]
	v_mfma_f32_16x16x32_bf16 v[56:59], v[164:167], v[188:191], v[56:59]
	v_mfma_f32_16x16x32_bf16 v[44:47], v[156:159], v[196:199], v[44:47]
	v_mfma_f32_16x16x32_bf16 v[40:43], v[164:167], v[196:199], v[40:43]
	v_mfma_f32_16x16x32_bf16 v[28:31], v[156:159], v[204:207], v[28:31]
	v_mfma_f32_16x16x32_bf16 v[24:27], v[164:167], v[204:207], v[24:27]
	v_mfma_f32_16x16x32_bf16 v[12:15], v[156:159], v[218:221], v[12:15]
	v_mfma_f32_16x16x32_bf16 v[8:11], v[164:167], v[218:221], v[8:11]
	s_setprio 0
	s_setprio 1
	v_mfma_f32_16x16x32_bf16 v[52:55], v[168:171], v[184:187], v[52:55]
	v_mfma_f32_16x16x32_bf16 v[48:51], v[176:179], v[184:187], v[48:51]
	v_mfma_f32_16x16x32_bf16 v[36:39], v[168:171], v[192:195], v[36:39]
	v_mfma_f32_16x16x32_bf16 v[32:35], v[176:179], v[192:195], v[32:35]
	v_mfma_f32_16x16x32_bf16 v[20:23], v[168:171], v[200:203], v[20:23]
	v_mfma_f32_16x16x32_bf16 v[16:19], v[176:179], v[200:203], v[16:19]
	v_mfma_f32_16x16x32_bf16 v[4:7], v[168:171], v[208:211], v[4:7]
	v_mfma_f32_16x16x32_bf16 v[0:3], v[176:179], v[208:211], v[0:3]
	v_mfma_f32_16x16x32_bf16 v[52:55], v[172:175], v[188:191], v[52:55]
	v_mfma_f32_16x16x32_bf16 v[48:51], v[180:183], v[188:191], v[48:51]
	v_mfma_f32_16x16x32_bf16 v[36:39], v[172:175], v[196:199], v[36:39]
	v_mfma_f32_16x16x32_bf16 v[32:35], v[180:183], v[196:199], v[32:35]
	v_mfma_f32_16x16x32_bf16 v[20:23], v[172:175], v[204:207], v[20:23]
	v_mfma_f32_16x16x32_bf16 v[16:19], v[180:183], v[204:207], v[16:19]
	v_mfma_f32_16x16x32_bf16 v[4:7], v[172:175], v[218:221], v[4:7]
	v_mfma_f32_16x16x32_bf16 v[0:3], v[180:183], v[218:221], v[0:3]
	s_setprio 0
	s_barrier
	s_add_i32 s95, 0, 0x18000
	s_add_i32 s96, 0, 0x1c000
	v_add_u32_e32 v164, s95, v154
	v_add_u32_e32 v180, s96, v154
	ds_read_b128 v[128:131], v164
	ds_read_b128 v[156:159], v164 offset:1024
	ds_read_b128 v[160:163], v164 offset:2048
	ds_read_b128 v[164:167], v164 offset:3072
	ds_read_b128 v[168:171], v180
	ds_read_b128 v[172:175], v180 offset:1024
	ds_read_b128 v[176:179], v180 offset:2048
	ds_read_b128 v[180:183], v180 offset:3072
	s_add_u32 s8, s70, 0x40000
	s_addc_u32 s9, s71, 0
	s_mov_b32 m0, s77
	v_lshl_add_u64 v[228:229], s[8:9], 0, v[138:139]
	ds_read_b128 v[184:187], v155 offset:32768
	ds_read_b128 v[188:191], v155 offset:33792
	ds_read_b128 v[192:195], v155 offset:34816
	ds_read_b128 v[196:199], v155 offset:35840
	ds_read_b128 v[200:203], v155 offset:36864
	ds_read_b128 v[204:207], v155 offset:37888
	ds_read_b128 v[208:211], v155 offset:38912
	ds_read_b128 v[218:221], v155 offset:39936
	global_load_lds_dwordx4 v[228:229], off
	v_lshl_add_u64 v[228:229], s[8:9], 0, v[134:135]
	s_mov_b32 m0, s78
	s_nop 0
	global_load_lds_dwordx4 v[228:229], off
	s_waitcnt vmcnt(8)
	s_waitcnt lgkmcnt(0)
	s_barrier
	s_setprio 1
	s_waitcnt lgkmcnt(0)
	v_mfma_f32_16x16x32_bf16 v[124:127], v[128:131], v[184:187], v[124:127]
	v_mfma_f32_16x16x32_bf16 v[120:123], v[160:163], v[184:187], v[120:123]
	v_mfma_f32_16x16x32_bf16 v[108:111], v[128:131], v[192:195], v[108:111]
	v_mfma_f32_16x16x32_bf16 v[104:107], v[160:163], v[192:195], v[104:107]
	v_mfma_f32_16x16x32_bf16 v[92:95], v[128:131], v[200:203], v[92:95]
	v_mfma_f32_16x16x32_bf16 v[88:91], v[160:163], v[200:203], v[88:91]
	v_mfma_f32_16x16x32_bf16 v[76:79], v[128:131], v[208:211], v[76:79]
	v_mfma_f32_16x16x32_bf16 v[72:75], v[160:163], v[208:211], v[72:75]
	v_mfma_f32_16x16x32_bf16 v[124:127], v[156:159], v[188:191], v[124:127]
	v_mfma_f32_16x16x32_bf16 v[120:123], v[164:167], v[188:191], v[120:123]
	v_mfma_f32_16x16x32_bf16 v[108:111], v[156:159], v[196:199], v[108:111]
	v_mfma_f32_16x16x32_bf16 v[104:107], v[164:167], v[196:199], v[104:107]
	v_mfma_f32_16x16x32_bf16 v[92:95], v[156:159], v[204:207], v[92:95]
	v_mfma_f32_16x16x32_bf16 v[88:91], v[164:167], v[204:207], v[88:91]
	v_mfma_f32_16x16x32_bf16 v[76:79], v[156:159], v[218:221], v[76:79]
	v_mfma_f32_16x16x32_bf16 v[72:75], v[164:167], v[218:221], v[72:75]
	s_setprio 0
	s_setprio 1
	v_mfma_f32_16x16x32_bf16 v[116:119], v[168:171], v[184:187], v[116:119]
	v_mfma_f32_16x16x32_bf16 v[112:115], v[176:179], v[184:187], v[112:115]
	v_mfma_f32_16x16x32_bf16 v[100:103], v[168:171], v[192:195], v[100:103]
	v_mfma_f32_16x16x32_bf16 v[96:99], v[176:179], v[192:195], v[96:99]
	v_mfma_f32_16x16x32_bf16 v[84:87], v[168:171], v[200:203], v[84:87]
	v_mfma_f32_16x16x32_bf16 v[80:83], v[176:179], v[200:203], v[80:83]
	v_mfma_f32_16x16x32_bf16 v[68:71], v[168:171], v[208:211], v[68:71]
	v_mfma_f32_16x16x32_bf16 v[64:67], v[176:179], v[208:211], v[64:67]
	v_mfma_f32_16x16x32_bf16 v[116:119], v[172:175], v[188:191], v[116:119]
	v_mfma_f32_16x16x32_bf16 v[112:115], v[180:183], v[188:191], v[112:115]
	v_mfma_f32_16x16x32_bf16 v[100:103], v[172:175], v[196:199], v[100:103]
	v_mfma_f32_16x16x32_bf16 v[96:99], v[180:183], v[196:199], v[96:99]
	v_mfma_f32_16x16x32_bf16 v[84:87], v[172:175], v[204:207], v[84:87]
	v_mfma_f32_16x16x32_bf16 v[80:83], v[180:183], v[204:207], v[80:83]
	v_mfma_f32_16x16x32_bf16 v[68:71], v[172:175], v[218:221], v[68:71]
	v_mfma_f32_16x16x32_bf16 v[64:67], v[180:183], v[218:221], v[64:67]
	s_setprio 0
	s_barrier
; #define PG8_STAGE(bufoff, gbase, voff) do { _Pragma("unroll") for (int _i = 0; _i < 2; ++_i) \
;         __builtin_amdgcn_global_load_lds((const unsigned*)((const char*)(gbase) + (voff)[_i]), (PG8_LAS unsigned*)(lds + (bufoff) + ldsw + _i * 8192), 16, 0, 0); } while (0)
; #define PG8_LDA(dst, b, h) do { _Pragma("unroll") for (int m = 0; m < 4; ++m) _Pragma("unroll") for (int k = 0; k < 2; ++k) dst[m][k] = *(const PG8_LAS bf16x8*)(lds + PG8_SA(b, h) + aoff + m * 2048 + k * 1024); } while (0)
; #define PG8_MMA(ai, bj, At, Bt) do { __builtin_amdgcn_s_setprio(1); _Pragma("unroll") for (int m = 0; m < 4; ++m) _Pragma("unroll") for (int n = 0; n < 2; ++n) _Pragma("unroll") for (int k = 0; k < 2; ++k) \
;         acc[ai][bj][m][n] = __builtin_amdgcn_mfma_f32_16x16x32_bf16(Bt[n][k], At[m][k], acc[ai][bj][m][n], 0, 0, 0); __builtin_amdgcn_s_setprio(0); } while (0)
; #define PG8_WAIT_V(n) asm volatile("s_waitcnt vmcnt(" #n ")" ::: "memory")
; #define PG8_WAIT_L(n) asm volatile("s_waitcnt lgkmcnt(" #n ")" ::: "memory")
; #define PG8_BAR __builtin_amdgcn_s_barrier()
; #define PG8_SCHED __builtin_amdgcn_sched_barrier(0)
;     __device__ __forceinline__ void scale(f32x4 (&acc)[2][2][4][2], const Unit& u, int wr, int wc, int fr, int fq, int goff) const {
;         asm volatile("" : "+v"(fr), "+v"(fq));
;         const int row0 = u.pm * BM + wr * 64 + fr, col0 = u.pn * BM + wc * 32 + 8 * fq;
; #pragma unroll
;         for (int ai = 0; ai < 2; ++ai)
; #pragma unroll
;             for (int m = 0; m < 4; ++m) { const size_t row = (size_t)(row0 + ai * HALF + m * 16);
; #pragma unroll
;                 for (int bj = 0; bj < 2; ++bj) { const u32x4 g = __builtin_nontemporal_load((const u32x4*)(G + row * 2048 + goff + col0 + bj * HALF));
; template <class Epi, class Sched, bool ALIGN_EPI = false, bool SP2 = false>
; __device__ __forceinline__ void gemm_phase(PG8_LAS unsigned char* lds, const Gemm g, const Sched& S, const Epi& E, const int wave_s) {
;     ...
;             PG8_LDA(At, 1, 1); PG8_STAGE(PG8_SB(1, 0), b3, voffB); PG8_STAGE(PG8_SB(1, 1), b3 + hB, voffB); PG8_STAGE(PG8_SA(1, 0), a3, voffA);
;             PG8_WAIT_V(8); PG8_WAIT_L(0); PG8_BAR; PG8_MMA(1, 0, At, B0); PG8_MMA(1, 1, At, B1); PG8_BAR; PG8_SCHED;
	s_add_i32 s8, s95, s72
	v_lshl_add_u64 v[212:213], v[212:213], 0, s[6:7]
	s_mov_b32 m0, s8
	ds_read_b128 v[184:187], v155 offset:49152
	ds_read_b128 v[188:191], v155 offset:50176
	ds_read_b128 v[192:195], v155 offset:51200
	ds_read_b128 v[196:199], v155 offset:52224
	ds_read_b128 v[200:203], v155 offset:53248
	ds_read_b128 v[204:207], v155 offset:54272
	ds_read_b128 v[208:211], v155 offset:55296
	ds_read_b128 v[218:221], v155 offset:56320
	global_load_lds_dwordx4 v[212:213], off
	s_add_i32 m0, s8, 0x2000
	s_add_u32 s8, s68, 0x40080
	v_lshl_add_u64 v[212:213], v[222:223], 0, s[6:7]
	s_addc_u32 s9, s69, 0
	s_add_i32 s68, s96, s72
	global_load_lds_dwordx4 v[212:213], off
	v_lshl_add_u64 v[212:213], s[8:9], 0, v[136:137]
	s_mov_b32 m0, s68
	s_nop 0
	global_load_lds_dwordx4 v[212:213], off
	v_lshl_add_u64 v[212:213], s[8:9], 0, v[132:133]
	s_add_i32 m0, s68, 0x2000
	s_nop 0
	global_load_lds_dwordx4 v[212:213], off
	v_lshl_add_u64 v[212:213], v[224:225], 0, s[6:7]
	s_mov_b32 m0, s81
	s_nop 0
	global_load_lds_dwordx4 v[212:213], off
	v_lshl_add_u64 v[212:213], v[226:227], 0, s[6:7]
	s_mov_b32 m0, s82
	s_nop 0
	global_load_lds_dwordx4 v[212:213], off
	s_waitcnt vmcnt(8)
	s_waitcnt lgkmcnt(0)
	s_barrier
	s_setprio 1
	s_waitcnt lgkmcnt(0)
	v_mfma_f32_16x16x32_bf16 v[60:63], v[128:131], v[184:187], v[60:63]
	v_mfma_f32_16x16x32_bf16 v[56:59], v[160:163], v[184:187], v[56:59]
	v_mfma_f32_16x16x32_bf16 v[44:47], v[128:131], v[192:195], v[44:47]
	v_mfma_f32_16x16x32_bf16 v[40:43], v[160:163], v[192:195], v[40:43]
	v_mfma_f32_16x16x32_bf16 v[28:31], v[128:131], v[200:203], v[28:31]
	v_mfma_f32_16x16x32_bf16 v[24:27], v[160:163], v[200:203], v[24:27]
	v_mfma_f32_16x16x32_bf16 v[12:15], v[128:131], v[208:211], v[12:15]
	v_mfma_f32_16x16x32_bf16 v[8:11], v[160:163], v[208:211], v[8:11]
	v_mfma_f32_16x16x32_bf16 v[60:63], v[156:159], v[188:191], v[60:63]
	v_mfma_f32_16x16x32_bf16 v[56:59], v[164:167], v[188:191], v[56:59]
	v_mfma_f32_16x16x32_bf16 v[44:47], v[156:159], v[196:199], v[44:47]
	v_mfma_f32_16x16x32_bf16 v[40:43], v[164:167], v[196:199], v[40:43]
	v_mfma_f32_16x16x32_bf16 v[28:31], v[156:159], v[204:207], v[28:31]
	v_mfma_f32_16x16x32_bf16 v[24:27], v[164:167], v[204:207], v[24:27]
	v_mfma_f32_16x16x32_bf16 v[12:15], v[156:159], v[218:221], v[12:15]
	v_mfma_f32_16x16x32_bf16 v[8:11], v[164:167], v[218:221], v[8:11]
	s_setprio 0
	s_setprio 1
	v_mfma_f32_16x16x32_bf16 v[52:55], v[168:171], v[184:187], v[52:55]
	v_mfma_f32_16x16x32_bf16 v[48:51], v[176:179], v[184:187], v[48:51]
	v_mfma_f32_16x16x32_bf16 v[36:39], v[168:171], v[192:195], v[36:39]
	v_mfma_f32_16x16x32_bf16 v[32:35], v[176:179], v[192:195], v[32:35]
	v_mfma_f32_16x16x32_bf16 v[20:23], v[168:171], v[200:203], v[20:23]
	v_mfma_f32_16x16x32_bf16 v[16:19], v[176:179], v[200:203], v[16:19]
	v_mfma_f32_16x16x32_bf16 v[4:7], v[168:171], v[208:211], v[4:7]
	v_mfma_f32_16x16x32_bf16 v[0:3], v[176:179], v[208:211], v[0:3]
	v_mfma_f32_16x16x32_bf16 v[52:55], v[172:175], v[188:191], v[52:55]
	v_mfma_f32_16x16x32_bf16 v[48:51], v[180:183], v[188:191], v[48:51]
	v_mfma_f32_16x16x32_bf16 v[36:39], v[172:175], v[196:199], v[36:39]
	v_mfma_f32_16x16x32_bf16 v[32:35], v[180:183], v[196:199], v[32:35]
	v_mfma_f32_16x16x32_bf16 v[20:23], v[172:175], v[204:207], v[20:23]
	v_mfma_f32_16x16x32_bf16 v[16:19], v[180:183], v[204:207], v[16:19]
	v_mfma_f32_16x16x32_bf16 v[4:7], v[172:175], v[218:221], v[4:7]
	v_mfma_f32_16x16x32_bf16 v[0:3], v[180:183], v[218:221], v[0:3]
	s_setprio 0
	s_cmpk_lg_i32 s66, 0x300
	s_cbranch_scc1 .Lmid_early_skip
	v_mov_b32_e32 v129, v152
	v_mov_b32_e32 v128, v153
	v_add_u32_e32 v130, s51, v129
	v_ashrrev_i32_e32 v131, 31, v130
	v_lshl_add_u32 v128, v128, 3, s49
	v_lshlrev_b64 v[130:131], 12, v[130:131]
	v_ashrrev_i32_e32 v129, 31, v128
	v_lshl_add_u64 v[130:131], s[20:21], 0, v[130:131]
	v_lshl_add_u64 v[128:129], v[128:129], 1, v[130:131]
	global_load_dwordx4 v[164:167], v[128:129], off nt
	global_load_dwordx4 v[168:171], v[128:129], off offset:256 nt
	s_mov_b32 s99, 0
	s_mov_b32 s98, 0x10000
	v_lshl_add_u64 v[162:163], v[128:129], 0, s[98:99]
	global_load_dwordx4 v[172:175], v[162:163], off nt
	global_load_dwordx4 v[176:179], v[162:163], off offset:256 nt
	s_mov_b32 s98, 0x20000
	v_lshl_add_u64 v[162:163], v[128:129], 0, s[98:99]
	global_load_dwordx4 v[180:183], v[162:163], off nt
	global_load_dwordx4 v[184:187], v[162:163], off offset:256 nt
	s_mov_b32 s98, 0x30000
	v_lshl_add_u64 v[162:163], v[128:129], 0, s[98:99]
	global_load_dwordx4 v[188:191], v[162:163], off nt
	global_load_dwordx4 v[192:195], v[162:163], off offset:256 nt
	s_mov_b32 s98, 0x80000
	v_lshl_add_u64 v[162:163], v[128:129], 0, s[98:99]
	global_load_dwordx4 v[196:199], v[162:163], off nt
	global_load_dwordx4 v[200:203], v[162:163], off offset:256 nt
	s_mov_b32 s98, 0x90000
	v_lshl_add_u64 v[162:163], v[128:129], 0, s[98:99]
	global_load_dwordx4 v[204:207], v[162:163], off nt
	global_load_dwordx4 v[208:211], v[162:163], off offset:256 nt
	s_mov_b32 s98, 0xa0000
	v_lshl_add_u64 v[162:163], v[128:129], 0, s[98:99]
	global_load_dwordx4 v[218:221], v[162:163], off nt
	global_load_dwordx4 v[232:235], v[162:163], off offset:256 nt
	s_mov_b32 s98, 0xb0000
	v_lshl_add_u64 v[162:163], v[128:129], 0, s[98:99]
	global_load_dwordx4 v[236:239], v[162:163], off nt
	global_load_dwordx4 v[240:243], v[162:163], off offset:256 nt
